# DIFF epilogue: the remaining xor-16 hop of the 16 subln row reductions done with v_permlane16_swap + add instead of ds_bpermute (no LDS round trips left in the reductions)
# speedup vs baseline: 1.0009x; 1.0009x over previous
; __device__ __forceinline__ unsigned f2bf(float f) { unsigned u = __builtin_bit_cast(unsigned, f); return (u + 0x7fffu + ((u >> 16) & 1u)) >> 16; }
; __device__ __forceinline__ int crow(int r, int hi) { return (r & 3) + 8 * (r >> 2) + 4 * hi; }
; #define GATE_LOAD(NIT, RB) do { _Pragma("unroll") for (int i_ = 0; i_ < (NIT); ++i_) { const int idx_ = i_ * 64 + lane, row_ = (RB) + (idx_ >> 4), ch_ = idx_ & 15; \
;       gv[i_] = *(const u32x4*)(P.Gw + (long)row_ * 2048 + ch_ * 8); } } while (0)
; template <int DQK, int KW, bool DIFF, int SDEPTH, int QSP, int NBUF>
; __device__ __forceinline__ void attn_unit(const UnitP& P, char* lds) {
;     ...
;     GATE_LOAD(4, (wid >> 2) * 16);
;     if (wid < 4) {
;       float sg[4];
; #pragma unroll
;       for (int d0 = 0; d0 < 4; ++d0) sg[d0] = P.subg[d0 * 32 + r32] * P.osc;
; #pragma unroll
;       for (int r = 0; r < 16; ++r) { float ss = 0.f;
; #pragma unroll
;         for (int d0 = 0; d0 < 4; ++d0) { const float v = o[d0][r] - P.lam * st[(d0 * 16 + r) * 64]; o[d0][r] = v; ss += v * v; }
;         ss += __shfl_xor(ss, 1); ss += __shfl_xor(ss, 2); ss += __shfl_xor(ss, 4); ss += __shfl_xor(ss, 8); ss += __shfl_xor(ss, 16);
;         const float rstd = __builtin_amdgcn_rsqf(ss * (1.f / 128.f) + NORM_EPS); const int ro = crow(r, hi) * 128 + r32;
; #pragma unroll
;         for (int d0 = 0; d0 < 4; ++d0) stgp[ro + d0 * 32] = (bf16_t)f2bf(o[d0][r] * rstd * sg[d0]); }
.LBB0_342:
	s_or_b64 exec, exec, s[8:9]
	s_lshl_b64 s[38:39], s[6:7], 1
	s_add_u32 s7, s22, s38
	s_addc_u32 s9, s23, s39
	s_lshl_b32 s6, s2, 1
	v_lshrrev_b32_e32 v4, 4, v177
	s_add_u32 s8, s7, s6
	v_lshl_or_b32 v32, v165, 4, v4
	s_addc_u32 s9, s9, 0
	v_ashrrev_i32_e32 v33, 31, v32
	v_or_b32_e32 v28, 4, v32
	v_or_b32_e32 v26, 8, v32
	v_or_b32_e32 v20, 12, v32
	v_lshl_add_u64 v[2:3], s[8:9], 0, v[0:1]
	v_lshlrev_b64 v[30:31], 12, v[32:33]
	v_ashrrev_i32_e32 v29, 31, v28
	v_ashrrev_i32_e32 v27, 31, v26
	v_ashrrev_i32_e32 v21, 31, v20
	v_lshl_add_u64 v[4:5], v[2:3], 0, v[30:31]
	v_lshlrev_b64 v[24:25], 12, v[28:29]
	v_lshlrev_b64 v[22:23], 12, v[26:27]
	v_lshlrev_b64 v[18:19], 12, v[20:21]
	s_waitcnt lgkmcnt(0)
	s_barrier
	v_lshl_add_u64 v[6:7], v[2:3], 0, v[24:25]
	global_load_dwordx4 v[14:17], v[4:5], off
	global_load_dwordx4 v[10:13], v[6:7], off
	v_lshl_add_u64 v[4:5], v[2:3], 0, v[22:23]
	v_lshl_add_u64 v[2:3], v[2:3], 0, v[18:19]
	global_load_dwordx4 v[6:9], v[4:5], off
	s_nop 0
	global_load_dwordx4 v[2:5], v[2:3], off
	s_add_i32 s2, 0, 0x10000
	v_lshl_add_u32 v21, v44, 1, s2
	v_cmp_gt_i32_e32 vcc, 4, v99
	s_and_saveexec_b64 s[42:43], vcc
	s_cbranch_execz .LBB0_310
	v_lshlrev_b32_e32 v44, 2, v162
	global_load_dword v27, v44, s[4:5]
	global_load_dword v29, v44, s[4:5] offset:128
	global_load_dword v33, v44, s[4:5] offset:256
	ds_read2st64_b32 v[102:103], v47 offset1:1
	ds_read2st64_b32 v[104:105], v47 offset0:16 offset1:17
	ds_read2st64_b32 v[106:107], v47 offset0:48 offset1:49
	global_load_dword v44, v44, s[4:5] offset:384
	v_lshlrev_b32_e32 v45, 10, v175
	v_lshlrev_b32_e32 v99, 1, v162
	v_add3_u32 v45, v21, v45, v99
	s_waitcnt lgkmcnt(2)
	v_fma_f32 v97, -v172, v102, v97
	s_waitcnt lgkmcnt(1)
	v_fma_f32 v102, -v172, v104, v98
	ds_read2st64_b32 v[98:99], v47 offset0:32 offset1:33
	v_mul_f32_e32 v104, v102, v102
	v_fmac_f32_e32 v104, v97, v97
	v_fma_f32 v95, -v172, v105, v95
	v_fma_f32 v94, -v172, v103, v94
	s_waitcnt lgkmcnt(0)
	v_fma_f32 v98, -v172, v98, v100
	v_fmac_f32_e32 v104, v98, v98
	v_fma_f32 v100, -v172, v106, v101
	v_fmac_f32_e32 v104, v100, v100
	s_nop 1
	v_add_f32_dpp v104, v104, v104 quad_perm:[1,0,3,2] row_mask:0xf bank_mask:0xf
	s_nop 1
	v_add_f32_dpp v104, v104, v104 quad_perm:[2,3,0,1] row_mask:0xf bank_mask:0xf
	s_nop 1
	v_add_f32_dpp v104, v104, v104 row_half_mirror row_mask:0xf bank_mask:0xf
	s_nop 1
	v_add_f32_dpp v104, v104, v104 row_mirror row_mask:0xf bank_mask:0xf
	v_fma_f32 v96, -v172, v99, v96
	v_fma_f32 v41, -v172, v107, v41
	s_waitcnt lgkmcnt(0)
	v_mov_b32_e32 v101, v104
	s_waitcnt lgkmcnt(0)
	s_waitcnt lgkmcnt(0)
	s_waitcnt lgkmcnt(0)
	v_mov_b32_e32 v104, v101
	s_nop 1
	v_permlane16_swap_b32_e32 v101, v104
	v_add_f32_e32 v101, v101, v104
	v_fmamk_f32 v101, v101, 0x3c000000, v186
	v_rsq_f32_e32 v101, v101
	s_waitcnt vmcnt(3)
	v_mul_f32_e32 v27, v173, v27
	v_mul_f32_e32 v97, v97, v101
	v_mul_f32_e32 v97, v27, v97
	v_bfe_u32 v104, v97, 16, 1
	v_add3_u32 v97, v97, v104, s85
	s_waitcnt vmcnt(2)
	v_mul_f32_e32 v29, v173, v29
	ds_write_b16_d16_hi v45, v97
	v_mul_f32_e32 v97, v102, v101
	v_mul_f32_e32 v97, v29, v97
	v_bfe_u32 v102, v97, 16, 1
	v_add3_u32 v97, v97, v102, s85
	s_waitcnt vmcnt(1)
	v_mul_f32_e32 v33, v173, v33
	ds_write_b16_d16_hi v45, v97 offset:64
	v_mul_f32_e32 v97, v98, v101
	v_mul_f32_e32 v97, v33, v97
	v_bfe_u32 v98, v97, 16, 1
	v_add3_u32 v97, v97, v98, s85
	s_waitcnt vmcnt(0)
	v_mul_f32_e32 v44, v173, v44
	ds_write_b16_d16_hi v45, v97 offset:128
	v_mul_f32_e32 v97, v100, v101
	v_mul_f32_e32 v97, v44, v97
	v_bfe_u32 v98, v97, 16, 1
	v_add3_u32 v97, v97, v98, s85
	ds_write_b16_d16_hi v45, v97 offset:192
	v_mul_f32_e32 v97, v95, v95
	v_fmac_f32_e32 v97, v94, v94
	v_fmac_f32_e32 v97, v96, v96
	v_fmac_f32_e32 v97, v41, v41
	s_nop 1
	v_add_f32_dpp v97, v97, v97 quad_perm:[1,0,3,2] row_mask:0xf bank_mask:0xf
	s_nop 1
	v_add_f32_dpp v97, v97, v97 quad_perm:[2,3,0,1] row_mask:0xf bank_mask:0xf
	s_nop 1
	v_add_f32_dpp v97, v97, v97 row_half_mirror row_mask:0xf bank_mask:0xf
	s_nop 1
	v_add_f32_dpp v97, v97, v97 row_mirror row_mask:0xf bank_mask:0xf
	s_waitcnt lgkmcnt(0)
	s_nop 0
	s_waitcnt lgkmcnt(0)
	s_waitcnt lgkmcnt(0)
	s_waitcnt lgkmcnt(0)
	v_mov_b32_e32 v98, v97
	s_nop 1
	v_permlane16_swap_b32_e32 v97, v98
	v_add_f32_e32 v97, v97, v98
	v_fmamk_f32 v97, v97, 0x3c000000, v186
	v_rsq_f32_e32 v97, v97
	s_nop 0
	v_mul_f32_e32 v94, v94, v97
	v_mul_f32_e32 v94, v27, v94
	v_bfe_u32 v98, v94, 16, 1
	v_add3_u32 v94, v94, v98, s85
	ds_write_b16_d16_hi v45, v94 offset:256
	v_mul_f32_e32 v94, v95, v97
	v_mul_f32_e32 v94, v29, v94
	v_bfe_u32 v95, v94, 16, 1
	v_add3_u32 v94, v94, v95, s85
	ds_write_b16_d16_hi v45, v94 offset:320
	v_mul_f32_e32 v94, v96, v97
	v_mul_f32_e32 v94, v33, v94
	v_bfe_u32 v95, v94, 16, 1
	v_mul_f32_e32 v41, v41, v97
	v_add3_u32 v94, v94, v95, s85
	v_mul_f32_e32 v41, v44, v41
	ds_write_b16_d16_hi v45, v94 offset:384
	v_bfe_u32 v94, v41, 16, 1
	v_add3_u32 v41, v41, v94, s85
	ds_read2st64_b32 v[94:95], v47 offset0:2 offset1:3
	ds_read2st64_b32 v[96:97], v47 offset0:18 offset1:19
	ds_read2st64_b32 v[98:99], v47 offset0:34 offset1:35
	ds_write_b16_d16_hi v45, v41 offset:448
	s_waitcnt lgkmcnt(3)
	v_fma_f32 v41, -v172, v94, v91
	s_waitcnt lgkmcnt(2)
	v_fma_f32 v91, -v172, v96, v92
	s_waitcnt lgkmcnt(1)
	v_fma_f32 v96, -v172, v98, v93
	ds_read2st64_b32 v[92:93], v47 offset0:50 offset1:51
	v_mul_f32_e32 v94, v91, v91
	v_fmac_f32_e32 v94, v41, v41
	v_fmac_f32_e32 v94, v96, v96
	s_waitcnt lgkmcnt(0)
; __device__ __forceinline__ unsigned f2bf(float f) { unsigned u = __builtin_bit_cast(unsigned, f); return (u + 0x7fffu + ((u >> 16) & 1u)) >> 16; }
; __device__ __forceinline__ int crow(int r, int hi) { return (r & 3) + 8 * (r >> 2) + 4 * hi; }
; template <int DQK, int KW, bool DIFF, int SDEPTH, int QSP, int NBUF>
; __device__ __forceinline__ void attn_unit(const UnitP& P, char* lds) {
;     ...
;       for (int r = 0; r < 16; ++r) { float ss = 0.f;
; #pragma unroll
;         for (int d0 = 0; d0 < 4; ++d0) { const float v = o[d0][r] - P.lam * st[(d0 * 16 + r) * 64]; o[d0][r] = v; ss += v * v; }
;         ss += __shfl_xor(ss, 1); ss += __shfl_xor(ss, 2); ss += __shfl_xor(ss, 4); ss += __shfl_xor(ss, 8); ss += __shfl_xor(ss, 16);
;         const float rstd = __builtin_amdgcn_rsqf(ss * (1.f / 128.f) + NORM_EPS); const int ro = crow(r, hi) * 128 + r32;
; #pragma unroll
;         for (int d0 = 0; d0 < 4; ++d0) stgp[ro + d0 * 32] = (bf16_t)f2bf(o[d0][r] * rstd * sg[d0]); }
	v_fma_f32 v39, -v172, v92, v39
	v_fmac_f32_e32 v94, v39, v39
	s_nop 1
	v_add_f32_dpp v94, v94, v94 quad_perm:[1,0,3,2] row_mask:0xf bank_mask:0xf
	s_nop 1
	v_add_f32_dpp v94, v94, v94 quad_perm:[2,3,0,1] row_mask:0xf bank_mask:0xf
	s_nop 1
	v_add_f32_dpp v94, v94, v94 row_half_mirror row_mask:0xf bank_mask:0xf
	s_nop 1
	v_add_f32_dpp v94, v94, v94 row_mirror row_mask:0xf bank_mask:0xf
	v_fma_f32 v38, -v172, v93, v38
	s_waitcnt lgkmcnt(0)
	v_mov_b32_e32 v92, v94
	s_waitcnt lgkmcnt(0)
	s_waitcnt lgkmcnt(0)
	s_waitcnt lgkmcnt(0)
	v_mov_b32_e32 v94, v92
	s_nop 1
	v_permlane16_swap_b32_e32 v92, v94
	v_add_f32_e32 v92, v92, v94
	v_fmamk_f32 v92, v92, 0x3c000000, v186
	v_rsq_f32_e32 v92, v92
	s_nop 0
	v_mul_f32_e32 v41, v41, v92
	v_mul_f32_e32 v41, v27, v41
	v_bfe_u32 v94, v41, 16, 1
	v_add3_u32 v41, v41, v94, s85
	ds_write_b16_d16_hi v45, v41 offset:512
	v_mul_f32_e32 v41, v91, v92
	v_mul_f32_e32 v41, v29, v41
	v_bfe_u32 v91, v41, 16, 1
	v_add3_u32 v41, v41, v91, s85
	ds_write_b16_d16_hi v45, v41 offset:576
	v_mul_f32_e32 v41, v96, v92
	v_mul_f32_e32 v41, v33, v41
	v_bfe_u32 v91, v41, 16, 1
	v_mul_f32_e32 v39, v39, v92
	v_add3_u32 v41, v41, v91, s85
	v_mul_f32_e32 v39, v44, v39
	ds_write_b16_d16_hi v45, v41 offset:640
	v_bfe_u32 v41, v39, 16, 1
	v_add3_u32 v39, v39, v41, s85
	v_fma_f32 v41, -v172, v97, v89
	ds_write_b16_d16_hi v45, v39 offset:704
	v_fma_f32 v39, -v172, v95, v88
	v_mul_f32_e32 v88, v41, v41
	v_fmac_f32_e32 v88, v39, v39
	v_fma_f32 v89, -v172, v99, v90
	v_fmac_f32_e32 v88, v89, v89
	v_fmac_f32_e32 v88, v38, v38
	s_nop 1
	v_add_f32_dpp v88, v88, v88 quad_perm:[1,0,3,2] row_mask:0xf bank_mask:0xf
	s_nop 1
	v_add_f32_dpp v88, v88, v88 quad_perm:[2,3,0,1] row_mask:0xf bank_mask:0xf
	s_nop 1
	v_add_f32_dpp v88, v88, v88 row_half_mirror row_mask:0xf bank_mask:0xf
	s_nop 1
	v_add_f32_dpp v88, v88, v88 row_mirror row_mask:0xf bank_mask:0xf
	s_waitcnt lgkmcnt(0)
	s_nop 0
	s_waitcnt lgkmcnt(0)
	s_waitcnt lgkmcnt(0)
	s_waitcnt lgkmcnt(0)
	v_mov_b32_e32 v90, v88
	s_nop 1
	v_permlane16_swap_b32_e32 v88, v90
	v_add_f32_e32 v88, v88, v90
	v_fmamk_f32 v88, v88, 0x3c000000, v186
	v_rsq_f32_e32 v88, v88
	s_nop 0
	v_mul_f32_e32 v39, v39, v88
	v_mul_f32_e32 v39, v27, v39
	v_bfe_u32 v90, v39, 16, 1
	v_add3_u32 v39, v39, v90, s85
	ds_write_b16_d16_hi v45, v39 offset:768
	v_mul_f32_e32 v39, v41, v88
	v_mul_f32_e32 v39, v29, v39
	v_bfe_u32 v41, v39, 16, 1
	v_add3_u32 v39, v39, v41, s85
	ds_write_b16_d16_hi v45, v39 offset:832
	v_mul_f32_e32 v39, v89, v88
	v_mul_f32_e32 v39, v33, v39
	v_bfe_u32 v41, v39, 16, 1
	v_mul_f32_e32 v38, v38, v88
	v_add3_u32 v39, v39, v41, s85
	v_mul_f32_e32 v38, v44, v38
	ds_write_b16_d16_hi v45, v39 offset:896
	v_bfe_u32 v39, v38, 16, 1
	v_add3_u32 v38, v38, v39, s85
	ds_write_b16_d16_hi v45, v38 offset:960
	ds_read2st64_b32 v[38:39], v47 offset0:4 offset1:5
	ds_read2st64_b32 v[88:89], v47 offset0:20 offset1:21
	ds_read2st64_b32 v[90:91], v47 offset0:52 offset1:53
	s_waitcnt lgkmcnt(2)
	v_fma_f32 v38, -v172, v38, v86
	s_waitcnt lgkmcnt(1)
	v_fma_f32 v41, -v172, v88, v87
	ds_read2st64_b32 v[86:87], v47 offset0:36 offset1:37
	v_mul_f32_e32 v88, v41, v41
	v_fmac_f32_e32 v88, v38, v38
	s_waitcnt lgkmcnt(1)
	v_fma_f32 v37, -v172, v90, v37
	v_fma_f32 v35, -v172, v91, v35
	s_waitcnt lgkmcnt(0)
	v_fma_f32 v36, -v172, v86, v36
	v_fmac_f32_e32 v88, v36, v36
	v_fmac_f32_e32 v88, v37, v37
	s_nop 1
	v_add_f32_dpp v88, v88, v88 quad_perm:[1,0,3,2] row_mask:0xf bank_mask:0xf
	s_nop 1
	v_add_f32_dpp v88, v88, v88 quad_perm:[2,3,0,1] row_mask:0xf bank_mask:0xf
	s_nop 1
	v_add_f32_dpp v88, v88, v88 row_half_mirror row_mask:0xf bank_mask:0xf
	s_nop 1
	v_add_f32_dpp v88, v88, v88 row_mirror row_mask:0xf bank_mask:0xf
	v_fma_f32 v34, -v172, v87, v34
	s_waitcnt lgkmcnt(0)
	v_mov_b32_e32 v86, v88
	s_waitcnt lgkmcnt(0)
	s_waitcnt lgkmcnt(0)
	s_waitcnt lgkmcnt(0)
	v_mov_b32_e32 v88, v86
	s_nop 1
	v_permlane16_swap_b32_e32 v86, v88
	v_add_f32_e32 v86, v86, v88
	v_fmamk_f32 v86, v86, 0x3c000000, v186
	v_rsq_f32_e32 v86, v86
	s_nop 0
	v_mul_f32_e32 v38, v38, v86
	v_mul_f32_e32 v38, v27, v38
	v_bfe_u32 v88, v38, 16, 1
	v_add3_u32 v38, v38, v88, s85
	ds_write_b16_d16_hi v45, v38 offset:2048
	v_mul_f32_e32 v38, v41, v86
	v_mul_f32_e32 v38, v29, v38
	v_bfe_u32 v41, v38, 16, 1
	v_mul_f32_e32 v36, v36, v86
	v_add3_u32 v38, v38, v41, s85
	v_mul_f32_e32 v36, v33, v36
	ds_write_b16_d16_hi v45, v38 offset:2112
	v_bfe_u32 v38, v36, 16, 1
	v_add3_u32 v36, v36, v38, s85
	ds_write_b16_d16_hi v45, v36 offset:2176
	v_mul_f32_e32 v36, v37, v86
	v_mul_f32_e32 v36, v44, v36
	v_bfe_u32 v37, v36, 16, 1
	v_add3_u32 v36, v36, v37, s85
	v_fma_f32 v37, -v172, v89, v85
	ds_write_b16_d16_hi v45, v36 offset:2240
	v_fma_f32 v36, -v172, v39, v84
	v_mul_f32_e32 v38, v37, v37
	v_fmac_f32_e32 v38, v36, v36
	v_fmac_f32_e32 v38, v34, v34
	v_fmac_f32_e32 v38, v35, v35
	s_nop 1
	v_add_f32_dpp v38, v38, v38 quad_perm:[1,0,3,2] row_mask:0xf bank_mask:0xf
	s_nop 1
	v_add_f32_dpp v38, v38, v38 quad_perm:[2,3,0,1] row_mask:0xf bank_mask:0xf
	s_nop 1
	v_add_f32_dpp v38, v38, v38 row_half_mirror row_mask:0xf bank_mask:0xf
	s_nop 1
	v_add_f32_dpp v38, v38, v38 row_mirror row_mask:0xf bank_mask:0xf
	s_waitcnt lgkmcnt(0)
	s_nop 0
	s_waitcnt lgkmcnt(0)
	s_waitcnt lgkmcnt(0)
	s_waitcnt lgkmcnt(0)
; __device__ __forceinline__ unsigned f2bf(float f) { unsigned u = __builtin_bit_cast(unsigned, f); return (u + 0x7fffu + ((u >> 16) & 1u)) >> 16; }
; __device__ __forceinline__ int crow(int r, int hi) { return (r & 3) + 8 * (r >> 2) + 4 * hi; }
; template <int DQK, int KW, bool DIFF, int SDEPTH, int QSP, int NBUF>
; __device__ __forceinline__ void attn_unit(const UnitP& P, char* lds) {
;     ...
;       for (int r = 0; r < 16; ++r) { float ss = 0.f;
; #pragma unroll
;         for (int d0 = 0; d0 < 4; ++d0) { const float v = o[d0][r] - P.lam * st[(d0 * 16 + r) * 64]; o[d0][r] = v; ss += v * v; }
;         ss += __shfl_xor(ss, 1); ss += __shfl_xor(ss, 2); ss += __shfl_xor(ss, 4); ss += __shfl_xor(ss, 8); ss += __shfl_xor(ss, 16);
;         const float rstd = __builtin_amdgcn_rsqf(ss * (1.f / 128.f) + NORM_EPS); const int ro = crow(r, hi) * 128 + r32;
; #pragma unroll
;         for (int d0 = 0; d0 < 4; ++d0) stgp[ro + d0 * 32] = (bf16_t)f2bf(o[d0][r] * rstd * sg[d0]); }
	v_mov_b32_e32 v39, v38
	s_nop 1
	v_permlane16_swap_b32_e32 v38, v39
	v_add_f32_e32 v38, v38, v39
	v_fmamk_f32 v38, v38, 0x3c000000, v186
	v_rsq_f32_e32 v38, v38
	s_nop 0
	v_mul_f32_e32 v36, v36, v38
	v_mul_f32_e32 v36, v27, v36
	v_bfe_u32 v39, v36, 16, 1
	v_add3_u32 v36, v36, v39, s85
	ds_write_b16_d16_hi v45, v36 offset:2304
	v_mul_f32_e32 v36, v37, v38
	v_mul_f32_e32 v36, v29, v36
	v_bfe_u32 v37, v36, 16, 1
	v_mul_f32_e32 v34, v34, v38
	v_add3_u32 v36, v36, v37, s85
	v_mul_f32_e32 v34, v33, v34
	ds_write_b16_d16_hi v45, v36 offset:2368
	v_bfe_u32 v36, v34, 16, 1
	v_add3_u32 v34, v34, v36, s85
	ds_write_b16_d16_hi v45, v34 offset:2432
	v_mul_f32_e32 v34, v35, v38
	v_mul_f32_e32 v34, v44, v34
	v_bfe_u32 v35, v34, 16, 1
	v_add3_u32 v34, v34, v35, s85
	ds_write_b16_d16_hi v45, v34 offset:2496
	ds_read2st64_b32 v[34:35], v47 offset0:6 offset1:7
	ds_read2st64_b32 v[36:37], v47 offset0:22 offset1:23
	ds_read2st64_b32 v[38:39], v47 offset0:38 offset1:39
	s_waitcnt lgkmcnt(2)
	v_fma_f32 v34, -v172, v34, v82
	s_waitcnt lgkmcnt(1)
	v_fma_f32 v36, -v172, v36, v83
	s_waitcnt lgkmcnt(0)
	v_fma_f32 v38, -v172, v38, v40
	ds_read2st64_b32 v[40:41], v47 offset0:54 offset1:55
	v_mul_f32_e32 v82, v36, v36
	v_fmac_f32_e32 v82, v34, v34
	v_fmac_f32_e32 v82, v38, v38
	s_waitcnt lgkmcnt(0)
	v_fma_f32 v40, -v172, v40, v81
	v_fmac_f32_e32 v82, v40, v40
	s_nop 1
	v_add_f32_dpp v82, v82, v82 quad_perm:[1,0,3,2] row_mask:0xf bank_mask:0xf
	s_nop 1
	v_add_f32_dpp v82, v82, v82 quad_perm:[2,3,0,1] row_mask:0xf bank_mask:0xf
	s_nop 1
	v_add_f32_dpp v82, v82, v82 row_half_mirror row_mask:0xf bank_mask:0xf
	s_nop 1
	v_add_f32_dpp v82, v82, v82 row_mirror row_mask:0xf bank_mask:0xf
	s_waitcnt lgkmcnt(0)
	v_mov_b32_e32 v81, v82
	s_waitcnt lgkmcnt(0)
	s_waitcnt lgkmcnt(0)
	s_waitcnt lgkmcnt(0)
	v_mov_b32_e32 v82, v81
	s_nop 1
	v_permlane16_swap_b32_e32 v81, v82
	v_add_f32_e32 v81, v81, v82
	v_fmamk_f32 v81, v81, 0x3c000000, v186
	v_rsq_f32_e32 v81, v81
	s_nop 0
	v_mul_f32_e32 v34, v34, v81
	v_mul_f32_e32 v34, v27, v34
	v_bfe_u32 v82, v34, 16, 1
	v_add3_u32 v34, v34, v82, s85
	ds_write_b16_d16_hi v45, v34 offset:2560
	v_mul_f32_e32 v34, v36, v81
	v_mul_f32_e32 v34, v29, v34
	v_bfe_u32 v36, v34, 16, 1
	v_add3_u32 v34, v34, v36, s85
	ds_write_b16_d16_hi v45, v34 offset:2624
	v_mul_f32_e32 v34, v38, v81
	v_mul_f32_e32 v34, v33, v34
	v_bfe_u32 v36, v34, 16, 1
	v_add3_u32 v34, v34, v36, s85
	ds_write_b16_d16_hi v45, v34 offset:2688
	v_mul_f32_e32 v34, v40, v81
	v_mul_f32_e32 v34, v44, v34
	v_bfe_u32 v36, v34, 16, 1
	v_add3_u32 v34, v34, v36, s85
	ds_write_b16_d16_hi v45, v34 offset:2752
	v_fma_f32 v34, -v172, v35, v77
	v_fma_f32 v35, -v172, v37, v78
	v_mul_f32_e32 v36, v35, v35
	v_fmac_f32_e32 v36, v34, v34
	v_fma_f32 v37, -v172, v39, v79
	v_fmac_f32_e32 v36, v37, v37
	v_fma_f32 v38, -v172, v41, v80
	v_fmac_f32_e32 v36, v38, v38
	s_nop 1
	v_add_f32_dpp v36, v36, v36 quad_perm:[1,0,3,2] row_mask:0xf bank_mask:0xf
	s_nop 1
	v_add_f32_dpp v36, v36, v36 quad_perm:[2,3,0,1] row_mask:0xf bank_mask:0xf
	s_nop 1
	v_add_f32_dpp v36, v36, v36 row_half_mirror row_mask:0xf bank_mask:0xf
	s_nop 1
	v_add_f32_dpp v36, v36, v36 row_mirror row_mask:0xf bank_mask:0xf
	ds_read2st64_b32 v[40:41], v47 offset0:56 offset1:57
	s_waitcnt lgkmcnt(0)
	s_nop 0
	s_waitcnt lgkmcnt(0)
	v_fma_f32 v40, -v172, v40, v76
	s_waitcnt lgkmcnt(0)
	s_waitcnt lgkmcnt(0)
	s_waitcnt lgkmcnt(0)
	v_mov_b32_e32 v39, v36
	s_nop 1
	v_permlane16_swap_b32_e32 v36, v39
	v_add_f32_e32 v36, v36, v39
	v_fmamk_f32 v36, v36, 0x3c000000, v186
	v_rsq_f32_e32 v36, v36
	s_nop 0
	v_mul_f32_e32 v34, v34, v36
	v_mul_f32_e32 v34, v27, v34
	v_bfe_u32 v39, v34, 16, 1
	v_add3_u32 v34, v34, v39, s85
	ds_write_b16_d16_hi v45, v34 offset:2816
	v_mul_f32_e32 v34, v35, v36
	v_mul_f32_e32 v34, v29, v34
	v_bfe_u32 v35, v34, 16, 1
	v_add3_u32 v34, v34, v35, s85
	ds_write_b16_d16_hi v45, v34 offset:2880
	v_mul_f32_e32 v34, v37, v36
	v_mul_f32_e32 v34, v33, v34
	v_bfe_u32 v35, v34, 16, 1
	v_add3_u32 v34, v34, v35, s85
	ds_write_b16_d16_hi v45, v34 offset:2944
	v_mul_f32_e32 v34, v38, v36
	v_mul_f32_e32 v34, v44, v34
	v_bfe_u32 v35, v34, 16, 1
	v_add3_u32 v34, v34, v35, s85
	ds_write_b16_d16_hi v45, v34 offset:3008
	ds_read2st64_b32 v[34:35], v47 offset0:8 offset1:9
	ds_read2st64_b32 v[36:37], v47 offset0:24 offset1:25
	ds_read2st64_b32 v[38:39], v47 offset0:40 offset1:41
	s_waitcnt lgkmcnt(2)
	v_fma_f32 v34, -v172, v34, v74
	s_waitcnt lgkmcnt(1)
	v_fma_f32 v36, -v172, v36, v75
	v_mul_f32_e32 v74, v36, v36
	v_fmac_f32_e32 v74, v34, v34
	s_waitcnt lgkmcnt(0)
	v_fma_f32 v38, -v172, v38, v65
	v_fmac_f32_e32 v74, v38, v38
	v_fmac_f32_e32 v74, v40, v40
	s_nop 1
	v_add_f32_dpp v74, v74, v74 quad_perm:[1,0,3,2] row_mask:0xf bank_mask:0xf
	s_nop 1
	v_add_f32_dpp v74, v74, v74 quad_perm:[2,3,0,1] row_mask:0xf bank_mask:0xf
	s_nop 1
	v_add_f32_dpp v74, v74, v74 row_half_mirror row_mask:0xf bank_mask:0xf
	s_nop 1
	v_add_f32_dpp v74, v74, v74 row_mirror row_mask:0xf bank_mask:0xf
	s_waitcnt lgkmcnt(0)
	v_mov_b32_e32 v65, v74
	s_waitcnt lgkmcnt(0)
	s_waitcnt lgkmcnt(0)
	s_waitcnt lgkmcnt(0)
; __device__ __forceinline__ unsigned f2bf(float f) { unsigned u = __builtin_bit_cast(unsigned, f); return (u + 0x7fffu + ((u >> 16) & 1u)) >> 16; }
; __device__ __forceinline__ int crow(int r, int hi) { return (r & 3) + 8 * (r >> 2) + 4 * hi; }
; template <int DQK, int KW, bool DIFF, int SDEPTH, int QSP, int NBUF>
; __device__ __forceinline__ void attn_unit(const UnitP& P, char* lds) {
;     ...
;       for (int r = 0; r < 16; ++r) { float ss = 0.f;
; #pragma unroll
;         for (int d0 = 0; d0 < 4; ++d0) { const float v = o[d0][r] - P.lam * st[(d0 * 16 + r) * 64]; o[d0][r] = v; ss += v * v; }
;         ss += __shfl_xor(ss, 1); ss += __shfl_xor(ss, 2); ss += __shfl_xor(ss, 4); ss += __shfl_xor(ss, 8); ss += __shfl_xor(ss, 16);
;         const float rstd = __builtin_amdgcn_rsqf(ss * (1.f / 128.f) + NORM_EPS); const int ro = crow(r, hi) * 128 + r32;
; #pragma unroll
;         for (int d0 = 0; d0 < 4; ++d0) stgp[ro + d0 * 32] = (bf16_t)f2bf(o[d0][r] * rstd * sg[d0]); }
	v_mov_b32_e32 v74, v65
	s_nop 1
	v_permlane16_swap_b32_e32 v65, v74
	v_add_f32_e32 v65, v65, v74
	v_fmamk_f32 v65, v65, 0x3c000000, v186
	v_rsq_f32_e32 v65, v65
	s_nop 0
	v_mul_f32_e32 v34, v34, v65
	v_mul_f32_e32 v34, v27, v34
	v_bfe_u32 v74, v34, 16, 1
	v_add3_u32 v34, v34, v74, s85
	ds_write_b16_d16_hi v45, v34 offset:4096
	v_mul_f32_e32 v34, v36, v65
	v_mul_f32_e32 v34, v29, v34
	v_bfe_u32 v36, v34, 16, 1
	v_add3_u32 v34, v34, v36, s85
	ds_write_b16_d16_hi v45, v34 offset:4160
	v_mul_f32_e32 v34, v38, v65
	v_mul_f32_e32 v34, v33, v34
	v_bfe_u32 v36, v34, 16, 1
	v_add3_u32 v34, v34, v36, s85
	ds_write_b16_d16_hi v45, v34 offset:4224
	v_mul_f32_e32 v34, v40, v65
	v_mul_f32_e32 v34, v44, v34
	v_bfe_u32 v36, v34, 16, 1
	v_add3_u32 v34, v34, v36, s85
	ds_write_b16_d16_hi v45, v34 offset:4288
	v_fma_f32 v34, -v172, v35, v72
	v_fma_f32 v35, -v172, v37, v73
	v_mul_f32_e32 v36, v35, v35
	v_fmac_f32_e32 v36, v34, v34
	v_fma_f32 v37, -v172, v39, v63
	v_fmac_f32_e32 v36, v37, v37
	v_fma_f32 v38, -v172, v41, v64
	v_fmac_f32_e32 v36, v38, v38
	s_nop 1
	v_add_f32_dpp v36, v36, v36 quad_perm:[1,0,3,2] row_mask:0xf bank_mask:0xf
	s_nop 1
	v_add_f32_dpp v36, v36, v36 quad_perm:[2,3,0,1] row_mask:0xf bank_mask:0xf
	s_nop 1
	v_add_f32_dpp v36, v36, v36 row_half_mirror row_mask:0xf bank_mask:0xf
	s_nop 1
	v_add_f32_dpp v36, v36, v36 row_mirror row_mask:0xf bank_mask:0xf
	ds_read2st64_b32 v[40:41], v47 offset0:58 offset1:59
	s_waitcnt lgkmcnt(0)
	s_nop 0
	s_waitcnt lgkmcnt(0)
	v_fma_f32 v40, -v172, v40, v62
	s_waitcnt lgkmcnt(0)
	s_waitcnt lgkmcnt(0)
	s_waitcnt lgkmcnt(0)
	v_mov_b32_e32 v39, v36
	s_nop 1
	v_permlane16_swap_b32_e32 v36, v39
	v_add_f32_e32 v36, v36, v39
	v_fmamk_f32 v36, v36, 0x3c000000, v186
	v_rsq_f32_e32 v36, v36
	s_nop 0
	v_mul_f32_e32 v34, v34, v36
	v_mul_f32_e32 v34, v27, v34
	v_bfe_u32 v39, v34, 16, 1
	v_add3_u32 v34, v34, v39, s85
	ds_write_b16_d16_hi v45, v34 offset:4352
	v_mul_f32_e32 v34, v35, v36
	v_mul_f32_e32 v34, v29, v34
	v_bfe_u32 v35, v34, 16, 1
	v_add3_u32 v34, v34, v35, s85
	ds_write_b16_d16_hi v45, v34 offset:4416
	v_mul_f32_e32 v34, v37, v36
	v_mul_f32_e32 v34, v33, v34
	v_bfe_u32 v35, v34, 16, 1
	v_add3_u32 v34, v34, v35, s85
	ds_write_b16_d16_hi v45, v34 offset:4480
	v_mul_f32_e32 v34, v38, v36
	v_mul_f32_e32 v34, v44, v34
	v_bfe_u32 v35, v34, 16, 1
	v_add3_u32 v34, v34, v35, s85
	ds_write_b16_d16_hi v45, v34 offset:4544
	ds_read2st64_b32 v[34:35], v47 offset0:10 offset1:11
	ds_read2st64_b32 v[36:37], v47 offset0:26 offset1:27
	ds_read2st64_b32 v[38:39], v47 offset0:42 offset1:43
	s_waitcnt lgkmcnt(2)
	v_fma_f32 v34, -v172, v34, v71
	s_waitcnt lgkmcnt(1)
	v_fma_f32 v36, -v172, v36, v60
	v_mul_f32_e32 v60, v36, v36
	v_fmac_f32_e32 v60, v34, v34
	s_waitcnt lgkmcnt(0)
	v_fma_f32 v38, -v172, v38, v61
	v_fmac_f32_e32 v60, v38, v38
	v_fmac_f32_e32 v60, v40, v40
	s_nop 1
	v_add_f32_dpp v60, v60, v60 quad_perm:[1,0,3,2] row_mask:0xf bank_mask:0xf
	s_nop 1
	v_add_f32_dpp v60, v60, v60 quad_perm:[2,3,0,1] row_mask:0xf bank_mask:0xf
	s_nop 1
	v_add_f32_dpp v60, v60, v60 row_half_mirror row_mask:0xf bank_mask:0xf
	s_nop 1
	v_add_f32_dpp v60, v60, v60 row_mirror row_mask:0xf bank_mask:0xf
	s_waitcnt lgkmcnt(0)
	s_nop 0
	s_waitcnt lgkmcnt(0)
	s_waitcnt lgkmcnt(0)
	s_waitcnt lgkmcnt(0)
	v_mov_b32_e32 v61, v60
	s_nop 1
	v_permlane16_swap_b32_e32 v60, v61
	v_add_f32_e32 v60, v60, v61
	v_fmamk_f32 v60, v60, 0x3c000000, v186
	v_rsq_f32_e32 v60, v60
	s_nop 0
	v_mul_f32_e32 v34, v34, v60
	v_mul_f32_e32 v34, v27, v34
	v_bfe_u32 v61, v34, 16, 1
	v_add3_u32 v34, v34, v61, s85
	ds_write_b16_d16_hi v45, v34 offset:4608
	v_mul_f32_e32 v34, v36, v60
	v_mul_f32_e32 v34, v29, v34
	v_bfe_u32 v36, v34, 16, 1
	v_add3_u32 v34, v34, v36, s85
	ds_write_b16_d16_hi v45, v34 offset:4672
	v_mul_f32_e32 v34, v38, v60
	v_mul_f32_e32 v34, v33, v34
	v_bfe_u32 v36, v34, 16, 1
	v_add3_u32 v34, v34, v36, s85
	ds_write_b16_d16_hi v45, v34 offset:4736
	v_mul_f32_e32 v34, v40, v60
	v_mul_f32_e32 v34, v44, v34
	v_bfe_u32 v36, v34, 16, 1
	v_add3_u32 v34, v34, v36, s85
	ds_write_b16_d16_hi v45, v34 offset:4800
	v_fma_f32 v34, -v172, v35, v70
	v_fma_f32 v35, -v172, v37, v57
	v_mul_f32_e32 v36, v35, v35
	v_fmac_f32_e32 v36, v34, v34
	v_fma_f32 v37, -v172, v39, v58
	v_fmac_f32_e32 v36, v37, v37
	v_fma_f32 v38, -v172, v41, v59
	v_fmac_f32_e32 v36, v38, v38
	s_nop 1
	v_add_f32_dpp v36, v36, v36 quad_perm:[1,0,3,2] row_mask:0xf bank_mask:0xf
	s_nop 1
	v_add_f32_dpp v36, v36, v36 quad_perm:[2,3,0,1] row_mask:0xf bank_mask:0xf
	s_nop 1
	v_add_f32_dpp v36, v36, v36 row_half_mirror row_mask:0xf bank_mask:0xf
	s_nop 1
	v_add_f32_dpp v36, v36, v36 row_mirror row_mask:0xf bank_mask:0xf
	ds_read2st64_b32 v[40:41], v47 offset0:60 offset1:61
	s_waitcnt lgkmcnt(0)
	s_nop 0
	s_waitcnt lgkmcnt(0)
	v_fma_f32 v40, -v172, v40, v56
	s_waitcnt lgkmcnt(0)
	s_waitcnt lgkmcnt(0)
	s_waitcnt lgkmcnt(0)
	v_mov_b32_e32 v39, v36
	s_nop 1
	v_permlane16_swap_b32_e32 v36, v39
	v_add_f32_e32 v36, v36, v39
	v_fmamk_f32 v36, v36, 0x3c000000, v186
	v_rsq_f32_e32 v36, v36
	s_nop 0
	v_mul_f32_e32 v34, v34, v36
	v_mul_f32_e32 v34, v27, v34
	v_bfe_u32 v39, v34, 16, 1
	v_add3_u32 v34, v34, v39, s85
	ds_write_b16_d16_hi v45, v34 offset:4864
	v_mul_f32_e32 v34, v35, v36
	v_mul_f32_e32 v34, v29, v34
	v_bfe_u32 v35, v34, 16, 1
	v_add3_u32 v34, v34, v35, s85
	ds_write_b16_d16_hi v45, v34 offset:4928
	v_mul_f32_e32 v34, v37, v36
	v_mul_f32_e32 v34, v33, v34
	v_bfe_u32 v35, v34, 16, 1
	v_add3_u32 v34, v34, v35, s85
	ds_write_b16_d16_hi v45, v34 offset:4992
	v_mul_f32_e32 v34, v38, v36
	v_mul_f32_e32 v34, v44, v34
	v_bfe_u32 v35, v34, 16, 1
	v_add3_u32 v34, v34, v35, s85
	ds_write_b16_d16_hi v45, v34 offset:5056
	ds_read2st64_b32 v[34:35], v47 offset0:12 offset1:13
	ds_read2st64_b32 v[36:37], v47 offset0:28 offset1:29
	ds_read2st64_b32 v[38:39], v47 offset0:44 offset1:45
	s_waitcnt lgkmcnt(2)
; __device__ __forceinline__ unsigned f2bf(float f) { unsigned u = __builtin_bit_cast(unsigned, f); return (u + 0x7fffu + ((u >> 16) & 1u)) >> 16; }
; __device__ __forceinline__ int crow(int r, int hi) { return (r & 3) + 8 * (r >> 2) + 4 * hi; }
; template <int DQK, int KW, bool DIFF, int SDEPTH, int QSP, int NBUF>
; __device__ __forceinline__ void attn_unit(const UnitP& P, char* lds) {
;     ...
;       for (int r = 0; r < 16; ++r) { float ss = 0.f;
; #pragma unroll
;         for (int d0 = 0; d0 < 4; ++d0) { const float v = o[d0][r] - P.lam * st[(d0 * 16 + r) * 64]; o[d0][r] = v; ss += v * v; }
;         ss += __shfl_xor(ss, 1); ss += __shfl_xor(ss, 2); ss += __shfl_xor(ss, 4); ss += __shfl_xor(ss, 8); ss += __shfl_xor(ss, 16);
;         const float rstd = __builtin_amdgcn_rsqf(ss * (1.f / 128.f) + NORM_EPS); const int ro = crow(r, hi) * 128 + r32;
; #pragma unroll
;         for (int d0 = 0; d0 < 4; ++d0) stgp[ro + d0 * 32] = (bf16_t)f2bf(o[d0][r] * rstd * sg[d0]); }
	v_fma_f32 v34, -v172, v34, v69
	s_waitcnt lgkmcnt(1)
	v_fma_f32 v36, -v172, v36, v54
	v_mul_f32_e32 v54, v36, v36
	v_fmac_f32_e32 v54, v34, v34
	s_waitcnt lgkmcnt(0)
	v_fma_f32 v38, -v172, v38, v55
	v_fmac_f32_e32 v54, v38, v38
	v_fmac_f32_e32 v54, v40, v40
	s_nop 1
	v_add_f32_dpp v54, v54, v54 quad_perm:[1,0,3,2] row_mask:0xf bank_mask:0xf
	s_nop 1
	v_add_f32_dpp v54, v54, v54 quad_perm:[2,3,0,1] row_mask:0xf bank_mask:0xf
	s_nop 1
	v_add_f32_dpp v54, v54, v54 row_half_mirror row_mask:0xf bank_mask:0xf
	s_nop 1
	v_add_f32_dpp v54, v54, v54 row_mirror row_mask:0xf bank_mask:0xf
	s_waitcnt lgkmcnt(0)
	s_nop 0
	s_waitcnt lgkmcnt(0)
	s_waitcnt lgkmcnt(0)
	s_waitcnt lgkmcnt(0)
	v_mov_b32_e32 v55, v54
	s_nop 1
	v_permlane16_swap_b32_e32 v54, v55
	v_add_f32_e32 v54, v54, v55
	v_fmamk_f32 v54, v54, 0x3c000000, v186
	v_rsq_f32_e32 v54, v54
	s_nop 0
	v_mul_f32_e32 v34, v34, v54
	v_mul_f32_e32 v34, v27, v34
	v_bfe_u32 v55, v34, 16, 1
	v_add3_u32 v34, v34, v55, s85
	ds_write_b16_d16_hi v45, v34 offset:6144
	v_mul_f32_e32 v34, v36, v54
	v_mul_f32_e32 v34, v29, v34
	v_bfe_u32 v36, v34, 16, 1
	v_add3_u32 v34, v34, v36, s85
	ds_write_b16_d16_hi v45, v34 offset:6208
	v_mul_f32_e32 v34, v38, v54
	v_mul_f32_e32 v34, v33, v34
	v_bfe_u32 v36, v34, 16, 1
	v_add3_u32 v34, v34, v36, s85
	ds_write_b16_d16_hi v45, v34 offset:6272
	v_mul_f32_e32 v34, v40, v54
	v_mul_f32_e32 v34, v44, v34
	v_bfe_u32 v36, v34, 16, 1
	v_add3_u32 v34, v34, v36, s85
	ds_write_b16_d16_hi v45, v34 offset:6336
	v_fma_f32 v34, -v172, v35, v68
	v_fma_f32 v35, -v172, v37, v52
	v_mul_f32_e32 v36, v35, v35
	v_fmac_f32_e32 v36, v34, v34
	v_fma_f32 v37, -v172, v39, v53
	v_fmac_f32_e32 v36, v37, v37
	v_fma_f32 v38, -v172, v41, v49
	v_fmac_f32_e32 v36, v38, v38
	s_nop 1
	v_add_f32_dpp v36, v36, v36 quad_perm:[1,0,3,2] row_mask:0xf bank_mask:0xf
	s_nop 1
	v_add_f32_dpp v36, v36, v36 quad_perm:[2,3,0,1] row_mask:0xf bank_mask:0xf
	s_nop 1
	v_add_f32_dpp v36, v36, v36 row_half_mirror row_mask:0xf bank_mask:0xf
	s_nop 1
	v_add_f32_dpp v36, v36, v36 row_mirror row_mask:0xf bank_mask:0xf
	ds_read2st64_b32 v[40:41], v47 offset0:62 offset1:63
	s_waitcnt lgkmcnt(0)
	s_nop 0
	s_waitcnt lgkmcnt(0)
	v_fma_f32 v40, -v172, v40, v46
	s_waitcnt lgkmcnt(0)
	s_waitcnt lgkmcnt(0)
	s_waitcnt lgkmcnt(0)
	v_mov_b32_e32 v39, v36
	s_nop 1
	v_permlane16_swap_b32_e32 v36, v39
	v_add_f32_e32 v36, v36, v39
	v_fmamk_f32 v36, v36, 0x3c000000, v186
	v_rsq_f32_e32 v36, v36
	s_nop 0
	v_mul_f32_e32 v34, v34, v36
	v_mul_f32_e32 v34, v27, v34
	v_bfe_u32 v39, v34, 16, 1
	v_add3_u32 v34, v34, v39, s85
	ds_write_b16_d16_hi v45, v34 offset:6400
	v_mul_f32_e32 v34, v35, v36
	v_mul_f32_e32 v34, v29, v34
	v_bfe_u32 v35, v34, 16, 1
	v_add3_u32 v34, v34, v35, s85
	ds_write_b16_d16_hi v45, v34 offset:6464
	v_mul_f32_e32 v34, v37, v36
	v_mul_f32_e32 v34, v33, v34
	v_bfe_u32 v35, v34, 16, 1
	v_add3_u32 v34, v34, v35, s85
	ds_write_b16_d16_hi v45, v34 offset:6528
	v_mul_f32_e32 v34, v38, v36
	v_mul_f32_e32 v34, v44, v34
	v_bfe_u32 v35, v34, 16, 1
	v_add3_u32 v34, v34, v35, s85
	ds_write_b16_d16_hi v45, v34 offset:6592
	ds_read2st64_b32 v[34:35], v47 offset0:14 offset1:15
	ds_read2st64_b32 v[36:37], v47 offset0:30 offset1:31
	ds_read2st64_b32 v[38:39], v47 offset0:46 offset1:47
	s_waitcnt lgkmcnt(2)
	v_fma_f32 v34, -v172, v34, v67
	s_waitcnt lgkmcnt(1)
	v_fma_f32 v36, -v172, v36, v51
	v_mul_f32_e32 v49, v36, v36
	v_fmac_f32_e32 v49, v34, v34
	s_waitcnt lgkmcnt(0)
	v_fma_f32 v38, -v172, v38, v48
	v_fmac_f32_e32 v49, v38, v38
	v_fmac_f32_e32 v49, v40, v40
	s_nop 1
	v_add_f32_dpp v49, v49, v49 quad_perm:[1,0,3,2] row_mask:0xf bank_mask:0xf
	s_nop 1
	v_add_f32_dpp v49, v49, v49 quad_perm:[2,3,0,1] row_mask:0xf bank_mask:0xf
	s_nop 1
	v_add_f32_dpp v49, v49, v49 row_half_mirror row_mask:0xf bank_mask:0xf
	s_nop 1
	v_add_f32_dpp v49, v49, v49 row_mirror row_mask:0xf bank_mask:0xf
	s_waitcnt lgkmcnt(0)
	v_mov_b32_e32 v46, v49
	s_waitcnt lgkmcnt(0)
	s_waitcnt lgkmcnt(0)
	s_waitcnt lgkmcnt(0)
	v_mov_b32_e32 v47, v46
	s_nop 1
	v_permlane16_swap_b32_e32 v46, v47
	v_add_f32_e32 v46, v46, v47
	v_fmamk_f32 v46, v46, 0x3c000000, v186
	v_rsq_f32_e32 v46, v46
	s_nop 0
	v_mul_f32_e32 v34, v34, v46
	v_mul_f32_e32 v34, v27, v34
	v_bfe_u32 v47, v34, 16, 1
	v_add3_u32 v34, v34, v47, s85
	ds_write_b16_d16_hi v45, v34 offset:6656
	v_mul_f32_e32 v34, v36, v46
	v_mul_f32_e32 v34, v29, v34
	v_bfe_u32 v36, v34, 16, 1
	v_add3_u32 v34, v34, v36, s85
	ds_write_b16_d16_hi v45, v34 offset:6720
	v_mul_f32_e32 v34, v38, v46
	v_mul_f32_e32 v34, v33, v34
	v_bfe_u32 v36, v34, 16, 1
	v_add3_u32 v34, v34, v36, s85
	ds_write_b16_d16_hi v45, v34 offset:6784
	v_mul_f32_e32 v34, v40, v46
	v_mul_f32_e32 v34, v44, v34
	v_bfe_u32 v36, v34, 16, 1
	v_add3_u32 v34, v34, v36, s85
	ds_write_b16_d16_hi v45, v34 offset:6848
	v_fma_f32 v34, -v172, v35, v66
	v_fma_f32 v35, -v172, v37, v50
	v_mul_f32_e32 v36, v35, v35
	v_fmac_f32_e32 v36, v34, v34
	v_fma_f32 v37, -v172, v39, v42
	v_fmac_f32_e32 v36, v37, v37
	v_fma_f32 v38, -v172, v41, v43
	v_fmac_f32_e32 v36, v38, v38
	s_nop 1
	v_add_f32_dpp v36, v36, v36 quad_perm:[1,0,3,2] row_mask:0xf bank_mask:0xf
	s_nop 1
	v_add_f32_dpp v36, v36, v36 quad_perm:[2,3,0,1] row_mask:0xf bank_mask:0xf
	s_nop 1
	v_add_f32_dpp v36, v36, v36 row_half_mirror row_mask:0xf bank_mask:0xf
	s_nop 1
	v_add_f32_dpp v36, v36, v36 row_mirror row_mask:0xf bank_mask:0xf
	s_waitcnt lgkmcnt(0)
	s_nop 0
	s_waitcnt lgkmcnt(0)
	s_waitcnt lgkmcnt(0)
	s_waitcnt lgkmcnt(0)
	v_mov_b32_e32 v39, v36
	s_nop 1
	v_permlane16_swap_b32_e32 v36, v39
	v_add_f32_e32 v36, v36, v39
	v_fmamk_f32 v36, v36, 0x3c000000, v186
	v_rsq_f32_e32 v36, v36
	s_nop 0
	v_mul_f32_e32 v34, v34, v36
	v_mul_f32_e32 v27, v27, v34
	v_bfe_u32 v34, v27, 16, 1
	v_add3_u32 v27, v27, v34, s85
	ds_write_b16_d16_hi v45, v27 offset:6912
	v_mul_f32_e32 v27, v35, v36
	v_mul_f32_e32 v27, v29, v27
	v_bfe_u32 v29, v27, 16, 1
	v_add3_u32 v27, v27, v29, s85
	ds_write_b16_d16_hi v45, v27 offset:6976
	v_mul_f32_e32 v27, v37, v36
	v_mul_f32_e32 v27, v33, v27
	v_bfe_u32 v29, v27, 16, 1
	v_add3_u32 v27, v27, v29, s85
	ds_write_b16_d16_hi v45, v27 offset:7040
	v_mul_f32_e32 v27, v38, v36
	v_mul_f32_e32 v27, v44, v27
	v_bfe_u32 v29, v27, 16, 1
	v_add3_u32 v27, v27, v29, s85
	ds_write_b16_d16_hi v45, v27 offset:7104
	s_branch .LBB0_310
